# SBA attention: tiles not masked for the wave take a copy of the probability section without the 16 per-element bit tests and selects (wave-uniform branch)
# speedup vs baseline: 1.0053x; 1.0053x over previous
; __device__ __forceinline__ void phase_sba_attn(const Params& p, u16* sm) {
;     ...
;       bf16x8 Lh[2], Ll[2];
; #pragma unroll
;       for (int k2 = 0; k2 < 2; ++k2) {
;         uint32_t hw[4], lw[4];
; #pragma unroll
;         for (int e2 = 0; e2 < 4; ++e2) {
;           const int mt = 2 * k2 + (e2 >> 1), j = (e2 & 1) * 2;
;           hw[e2] = pack2(L[mt][j], L[mt][j + 1]);
;           const float r0 = L[mt][j] - __uint_as_float(hw[e2] << 16), r1 = L[mt][j + 1] - __uint_as_float(hw[e2] & 0xffff0000u);
;           lw[e2] = pack2(r0, r1);
;         }
;         Lh[k2] = mk_frag(hw[0], hw[1], hw[2], hw[3]);
;         Ll[k2] = mk_frag(lw[0], lw[1], lw[2], lw[3]);
;       }
;       f32x4 cum[4];
; #pragma unroll
;       for (int ms = 0; ms < 4; ++ms) {
;         const int a = ms >> 1, bb = ms & 1;
;         f32x4 c = (f32x4){0.f, 0.f, 0.f, 0.f};
;         c = mfma16(tri[bb], Lh[a], c);
;         c = mfma16(tri[bb], Ll[a], c);
;         if (a == 0) { c = mfma16(ones, Lh[1], c); c = mfma16(ones, Ll[1], c); }
;         cum[ms] = c;
;       }
;       float tot = cum[0][0] + L[0][0];
;       tot = __shfl(tot, fr);
;       bf16x8 pf[2];
; #pragma unroll
;       for (int k2 = 0; k2 < 2; ++k2) {
;         uint32_t pw[4];
; #pragma unroll
;         for (int e2 = 0; e2 < 4; ++e2) {
;           const int mt = 2 * k2 + (e2 >> 1), j = (e2 & 1) * 2;
;           float p0 = __builtin_amdgcn_exp2f(lb[mt][j] + cum[mt][j] + carry);
;           float p1 = __builtin_amdgcn_exp2f(lb[mt][j + 1] + cum[mt][j + 1] + carry);
.LBB0_335:
	s_or_b64 exec, exec, s[8:9]
	s_nop 1
	v_cvt_pk_bf16_f32 v44, v2, v3
	v_lshlrev_b32_e32 v46, 16, v44
	v_and_b32_e32 v47, 0xffff0000, v44
	v_pk_add_f32 v[46:47], v[2:3], v[46:47] neg_lo:[0,1] neg_hi:[0,1]
	v_cvt_pk_bf16_f32 v45, v116, v117
	v_cvt_pk_bf16_f32 v48, v46, v47
	v_lshlrev_b32_e32 v3, 16, v45
	v_and_b32_e32 v46, 0xffff0000, v45
	v_sub_f32_e32 v3, v116, v3
	v_sub_f32_e32 v46, v117, v46
	v_cvt_pk_bf16_f32 v49, v3, v46
	v_cvt_pk_bf16_f32 v46, v118, v119
	v_lshlrev_b32_e32 v3, 16, v46
	v_and_b32_e32 v47, 0xffff0000, v46
	v_sub_f32_e32 v3, v118, v3
	v_sub_f32_e32 v47, v119, v47
	v_cvt_pk_bf16_f32 v50, v3, v47
	v_cvt_pk_bf16_f32 v47, v120, v121
	v_lshlrev_b32_e32 v3, 16, v47
	v_and_b32_e32 v51, 0xffff0000, v47
	v_sub_f32_e32 v3, v120, v3
	v_sub_f32_e32 v51, v121, v51
	v_cvt_pk_bf16_f32 v52, v123, v124
	v_cvt_pk_bf16_f32 v51, v3, v51
	v_lshlrev_b32_e32 v3, 16, v52
	v_and_b32_e32 v53, 0xffff0000, v52
	v_sub_f32_e32 v3, v123, v3
	v_sub_f32_e32 v53, v124, v53
	v_cvt_pk_bf16_f32 v56, v3, v53
	v_cvt_pk_bf16_f32 v53, v125, v126
	v_lshlrev_b32_e32 v3, 16, v53
	v_and_b32_e32 v54, 0xffff0000, v53
	v_sub_f32_e32 v3, v125, v3
	v_sub_f32_e32 v54, v126, v54
	v_cvt_pk_bf16_f32 v57, v3, v54
	v_cvt_pk_bf16_f32 v54, v127, v128
	v_mfma_f32_16x16x32_bf16 v[116:119], v[8:11], v[44:47], 0
	v_lshlrev_b32_e32 v3, 16, v54
	s_mov_b32 s18, s16
	s_mov_b32 s19, s16
	v_sub_f32_e32 v3, v127, v3
	s_mov_b32 s17, s16
	v_mov_b64_e32 v[126:127], s[18:19]
	v_mov_b64_e32 v[124:125], s[16:17]
	v_mfma_f32_16x16x32_bf16 v[116:119], v[8:11], v[48:51], v[116:119]
	v_and_b32_e32 v55, 0xffff0000, v54
	v_sub_f32_e32 v55, v128, v55
	v_cvt_pk_bf16_f32 v58, v3, v55
	v_mfma_f32_16x16x32_bf16 v[44:47], v[4:7], v[44:47], 0
	v_cvt_pk_bf16_f32 v55, v130, v129
	v_lshlrev_b32_e32 v3, 16, v55
	v_and_b32_e32 v59, 0xffff0000, v55
	v_mfma_f32_16x16x32_bf16 v[116:119], v[124:127], v[52:55], v[116:119]
	v_sub_f32_e32 v3, v130, v3
	v_sub_f32_e32 v59, v129, v59
	v_cvt_pk_bf16_f32 v59, v3, v59
	v_mfma_f32_16x16x32_bf16 v[44:47], v[4:7], v[48:51], v[44:47]
	s_nop 0
	v_mfma_f32_16x16x32_bf16 v[116:119], v[124:127], v[56:59], v[116:119]
	v_mfma_f32_16x16x32_bf16 v[44:47], v[124:127], v[52:55], v[44:47]
	v_mfma_f32_16x16x32_bf16 v[48:51], v[8:11], v[52:55], 0
	s_nop 5
	v_add_f32_e32 v3, v78, v116
	v_add_f32_e32 v3, v0, v3
	v_exp_f32_e32 v3, v3
	v_mfma_f32_16x16x32_bf16 v[52:55], v[4:7], v[52:55], 0
	v_add_f32_e32 v2, v2, v116
	ds_bpermute_b32 v2, v112, v2
	v_mfma_f32_16x16x32_bf16 v[44:47], v[124:127], v[56:59], v[44:47]
	v_mfma_f32_16x16x32_bf16 v[48:51], v[8:11], v[56:59], v[48:51]
	v_mfma_f32_16x16x32_bf16 v[52:55], v[4:7], v[56:59], v[52:55]
	v_add_f32_e32 v56, v79, v117
	v_add_f32_e32 v56, v0, v56
	v_exp_f32_e32 v56, v56
	s_andn2_b64 s[8:9], exec, vcc
	s_cbranch_scc0 .Lsba_um
; __device__ __forceinline__ void phase_sba_attn(const Params& p, u16* sm) {
;     ...
;       bf16x8 pf[2];
; #pragma unroll
;       for (int k2 = 0; k2 < 2; ++k2) {
;         uint32_t pw[4];
; #pragma unroll
;         for (int e2 = 0; e2 < 4; ++e2) {
;           const int mt = 2 * k2 + (e2 >> 1), j = (e2 & 1) * 2;
;           float p0 = __builtin_amdgcn_exp2f(lb[mt][j] + cum[mt][j] + carry);
;           float p1 = __builtin_amdgcn_exp2f(lb[mt][j + 1] + cum[mt][j + 1] + carry);
;           if (tile_masked) {
;             p0 = ((vmask >> (mt * 4 + j)) & 1u) ? p0 : 0.f;
;             p1 = ((vmask >> (mt * 4 + j + 1)) & 1u) ? p1 : 0.f;
;           }
;           pw[e2] = pack2(p0, p1);
;         }
;         pf[k2] = mk_frag(pw[0], pw[1], pw[2], pw[3]);
;       }
; #pragma unroll
;       for (int k2 = 0; k2 < 2; ++k2)
; #pragma unroll
;         for (int dm = 0; dm < 4; ++dm) {
;           bf16x8 vf = *(const bf16x8*)(sV + (dm * 16 + fr) * LDSP + k2 * 32 + fq * 8);
;           o[dm] = mfma16(vf, pf[k2], o[dm]);
;         }
;       carry += tot;
	v_and_b32_e32 v57, 1, v122
	v_cmp_eq_u32_e64 s[8:9], 1, v57
	v_and_b32_e32 v57, 2, v122
	v_cmp_ne_u32_e64 s[10:11], 0, v57
	s_or_b64 s[8:9], vcc, s[8:9]
	v_cndmask_b32_e64 v3, 0, v3, s[8:9]
	s_or_b64 s[8:9], vcc, s[10:11]
	v_cndmask_b32_e64 v56, 0, v56, s[8:9]
	v_cvt_pk_bf16_f32 v56, v3, v56
	v_add_f32_e32 v3, v80, v118
	v_add_f32_e32 v3, v0, v3
	v_add_f32_e32 v57, v81, v119
	v_exp_f32_e32 v3, v3
	v_add_f32_e32 v57, v0, v57
	v_exp_f32_e32 v57, v57
	v_and_b32_e32 v58, 4, v122
	v_cmp_ne_u32_e64 s[8:9], 0, v58
	v_and_b32_e32 v58, 8, v122
	v_cmp_ne_u32_e64 s[10:11], 0, v58
	s_or_b64 s[8:9], vcc, s[8:9]
	v_cndmask_b32_e64 v3, 0, v3, s[8:9]
	s_or_b64 s[8:9], vcc, s[10:11]
	v_cndmask_b32_e64 v57, 0, v57, s[8:9]
	v_cvt_pk_bf16_f32 v57, v3, v57
	v_add_f32_e32 v3, v82, v44
	v_add_f32_e32 v3, v0, v3
	v_add_f32_e32 v44, v83, v45
	v_exp_f32_e32 v3, v3
	v_add_f32_e32 v44, v0, v44
	v_exp_f32_e32 v44, v44
	v_and_b32_e32 v45, 16, v122
	v_cmp_ne_u32_e64 s[8:9], 0, v45
	v_and_b32_e32 v45, 32, v122
	v_cmp_ne_u32_e64 s[10:11], 0, v45
	s_or_b64 s[8:9], vcc, s[8:9]
	v_cndmask_b32_e64 v3, 0, v3, s[8:9]
	s_or_b64 s[8:9], vcc, s[10:11]
	v_cndmask_b32_e64 v44, 0, v44, s[8:9]
	v_cvt_pk_bf16_f32 v58, v3, v44
	v_add_f32_e32 v3, v84, v46
	v_add_f32_e32 v3, v0, v3
	v_add_f32_e32 v44, v85, v47
	v_exp_f32_e32 v3, v3
	v_add_f32_e32 v44, v0, v44
	v_exp_f32_e32 v44, v44
	v_and_b32_e32 v45, 64, v122
	v_cmp_ne_u32_e64 s[8:9], 0, v45
	v_and_b32_e32 v45, 0x80, v122
	v_cmp_ne_u32_e64 s[10:11], 0, v45
	s_or_b64 s[8:9], vcc, s[8:9]
	v_cndmask_b32_e64 v3, 0, v3, s[8:9]
	s_or_b64 s[8:9], vcc, s[10:11]
	v_cndmask_b32_e64 v44, 0, v44, s[8:9]
	v_cvt_pk_bf16_f32 v59, v3, v44
	v_add_f32_e32 v3, v86, v48
	v_add_f32_e32 v3, v0, v3
	v_add_f32_e32 v44, v87, v49
	v_exp_f32_e32 v3, v3
	v_add_f32_e32 v44, v0, v44
	v_exp_f32_e32 v44, v44
	v_and_b32_e32 v45, 0x100, v122
	v_cmp_ne_u32_e64 s[8:9], 0, v45
	v_and_b32_e32 v45, 0x200, v122
	v_cmp_ne_u32_e64 s[10:11], 0, v45
	s_or_b64 s[8:9], vcc, s[8:9]
	v_cndmask_b32_e64 v3, 0, v3, s[8:9]
	s_or_b64 s[8:9], vcc, s[10:11]
	v_cndmask_b32_e64 v44, 0, v44, s[8:9]
	v_cvt_pk_bf16_f32 v44, v3, v44
	v_add_f32_e32 v3, v88, v50
	v_add_f32_e32 v3, v0, v3
	v_add_f32_e32 v45, v89, v51
	v_exp_f32_e32 v3, v3
	v_add_f32_e32 v45, v0, v45
	v_exp_f32_e32 v45, v45
	v_and_b32_e32 v46, 0x400, v122
	v_cmp_ne_u32_e64 s[8:9], 0, v46
	v_and_b32_e32 v46, 0x800, v122
	v_cmp_ne_u32_e64 s[10:11], 0, v46
	s_or_b64 s[8:9], vcc, s[8:9]
	v_cndmask_b32_e64 v3, 0, v3, s[8:9]
	s_or_b64 s[8:9], vcc, s[10:11]
	v_cndmask_b32_e64 v45, 0, v45, s[8:9]
	v_cvt_pk_bf16_f32 v45, v3, v45
	v_add_f32_e32 v3, v90, v52
	v_add_f32_e32 v3, v0, v3
	v_add_f32_e32 v46, v91, v53
	v_exp_f32_e32 v3, v3
	v_add_f32_e32 v46, v0, v46
	v_exp_f32_e32 v46, v46
	v_and_b32_e32 v47, 0x1000, v122
	v_cmp_ne_u32_e64 s[8:9], 0, v47
	v_and_b32_e32 v47, 0x2000, v122
	v_cmp_ne_u32_e64 s[10:11], 0, v47
	s_or_b64 s[8:9], vcc, s[8:9]
	v_cndmask_b32_e64 v3, 0, v3, s[8:9]
	s_or_b64 s[8:9], vcc, s[10:11]
	v_cndmask_b32_e64 v46, 0, v46, s[8:9]
	v_cvt_pk_bf16_f32 v46, v3, v46
	v_add_f32_e32 v3, v92, v54
	ds_read_b128 v[48:51], v115 offset:9216
	v_add_f32_e32 v47, v93, v55
	ds_read_b128 v[52:55], v115 offset:11520
	ds_read_b128 v[78:81], v115 offset:13824
	ds_read_b128 v[82:85], v115 offset:9280
	v_and_b32_e32 v86, 0x4000, v122
	s_waitcnt lgkmcnt(2)
	v_mfma_f32_16x16x32_bf16 v[36:39], v[52:55], v[56:59], v[36:39]
	v_and_b32_e32 v52, 0x8000, v122
	v_cmp_ne_u32_e64 s[8:9], 0, v86
	v_cmp_ne_u32_e64 s[10:11], 0, v52
	v_mfma_f32_16x16x32_bf16 v[40:43], v[48:51], v[56:59], v[40:43]
	ds_read_b128 v[48:51], v115 offset:16128
	ds_read_b128 v[86:89], v115 offset:11584
	ds_read_b128 v[52:55], v115 offset:13888
	v_add_f32_e32 v3, v0, v3
	s_waitcnt lgkmcnt(4)
	v_mfma_f32_16x16x32_bf16 v[24:27], v[78:81], v[56:59], v[24:27]
	ds_read_b128 v[78:81], v115 offset:16192
	v_add_f32_e32 v47, v0, v47
	v_exp_f32_e32 v3, v3
	v_exp_f32_e32 v47, v47
	s_waitcnt lgkmcnt(3)
	v_mfma_f32_16x16x32_bf16 v[20:23], v[48:51], v[56:59], v[20:23]
	s_or_b64 s[8:9], vcc, s[8:9]
	s_or_b64 vcc, vcc, s[10:11]
	v_cndmask_b32_e64 v3, 0, v3, s[8:9]
	v_cndmask_b32_e32 v47, 0, v47, vcc
	v_cvt_pk_bf16_f32 v47, v3, v47
	v_add_f32_e32 v0, v0, v2
	s_nop 0
	v_mfma_f32_16x16x32_bf16 v[40:43], v[82:85], v[44:47], v[40:43]
	s_waitcnt lgkmcnt(2)
	v_mfma_f32_16x16x32_bf16 v[36:39], v[86:89], v[44:47], v[36:39]
	s_waitcnt lgkmcnt(1)
	v_mfma_f32_16x16x32_bf16 v[24:27], v[52:55], v[44:47], v[24:27]
	s_waitcnt lgkmcnt(0)
	v_mfma_f32_16x16x32_bf16 v[20:23], v[78:81], v[44:47], v[20:23]
	s_branch .LBB0_336
.Lsba_um:
	v_cvt_pk_bf16_f32 v56, v3, v56
	v_add_f32_e32 v3, v80, v118
	v_add_f32_e32 v3, v0, v3
	v_add_f32_e32 v57, v81, v119
	v_exp_f32_e32 v3, v3
	v_add_f32_e32 v57, v0, v57
	v_exp_f32_e32 v57, v57
	s_nop 0
	v_cvt_pk_bf16_f32 v57, v3, v57
	v_add_f32_e32 v3, v82, v44
	v_add_f32_e32 v3, v0, v3
	v_add_f32_e32 v44, v83, v45
	v_exp_f32_e32 v3, v3
	v_add_f32_e32 v44, v0, v44
	v_exp_f32_e32 v44, v44
	s_nop 0
	v_cvt_pk_bf16_f32 v58, v3, v44
	v_add_f32_e32 v3, v84, v46
	v_add_f32_e32 v3, v0, v3
	v_add_f32_e32 v44, v85, v47
	v_exp_f32_e32 v3, v3
	v_add_f32_e32 v44, v0, v44
	v_exp_f32_e32 v44, v44
	s_nop 0
	v_cvt_pk_bf16_f32 v59, v3, v44
	v_add_f32_e32 v3, v86, v48
	v_add_f32_e32 v3, v0, v3
	v_add_f32_e32 v44, v87, v49
	v_exp_f32_e32 v3, v3
	v_add_f32_e32 v44, v0, v44
	v_exp_f32_e32 v44, v44
	s_nop 0
	v_cvt_pk_bf16_f32 v44, v3, v44
	v_add_f32_e32 v3, v88, v50
	v_add_f32_e32 v3, v0, v3
	v_add_f32_e32 v45, v89, v51
	v_exp_f32_e32 v3, v3
	v_add_f32_e32 v45, v0, v45
	v_exp_f32_e32 v45, v45
	s_nop 0
	v_cvt_pk_bf16_f32 v45, v3, v45
	v_add_f32_e32 v3, v90, v52
	v_add_f32_e32 v3, v0, v3
	v_add_f32_e32 v46, v91, v53
	v_exp_f32_e32 v3, v3
	v_add_f32_e32 v46, v0, v46
	v_exp_f32_e32 v46, v46
	s_nop 0
	v_cvt_pk_bf16_f32 v46, v3, v46
	v_add_f32_e32 v3, v92, v54
	ds_read_b128 v[48:51], v115 offset:9216
	v_add_f32_e32 v47, v93, v55
	ds_read_b128 v[52:55], v115 offset:11520
	ds_read_b128 v[78:81], v115 offset:13824
	ds_read_b128 v[82:85], v115 offset:9280
	s_waitcnt lgkmcnt(2)
	v_mfma_f32_16x16x32_bf16 v[36:39], v[52:55], v[56:59], v[36:39]
	v_mfma_f32_16x16x32_bf16 v[40:43], v[48:51], v[56:59], v[40:43]
	ds_read_b128 v[48:51], v115 offset:16128
	ds_read_b128 v[86:89], v115 offset:11584
	ds_read_b128 v[52:55], v115 offset:13888
	v_add_f32_e32 v3, v0, v3
	s_waitcnt lgkmcnt(4)
	v_mfma_f32_16x16x32_bf16 v[24:27], v[78:81], v[56:59], v[24:27]
	ds_read_b128 v[78:81], v115 offset:16192
	v_add_f32_e32 v47, v0, v47
	v_exp_f32_e32 v3, v3
	v_exp_f32_e32 v47, v47
	s_waitcnt lgkmcnt(3)
	v_mfma_f32_16x16x32_bf16 v[20:23], v[48:51], v[56:59], v[20:23]
	v_cvt_pk_bf16_f32 v47, v3, v47
	v_add_f32_e32 v0, v0, v2
	s_nop 0
	v_mfma_f32_16x16x32_bf16 v[40:43], v[82:85], v[44:47], v[40:43]
	s_waitcnt lgkmcnt(2)
	v_mfma_f32_16x16x32_bf16 v[36:39], v[86:89], v[44:47], v[36:39]
	s_waitcnt lgkmcnt(1)
	v_mfma_f32_16x16x32_bf16 v[24:27], v[52:55], v[44:47], v[24:27]
	s_waitcnt lgkmcnt(0)
	v_mfma_f32_16x16x32_bf16 v[20:23], v[78:81], v[44:47], v[20:23]
